# kernel entry: all kernarg s_loads issued together before the first lgkmcnt wait (one scalar-memory round trip instead of two)
# baseline (speedup 1.0000x reference)
; #define LAS __attribute__((address_space(3)))
; __global__ void __launch_bounds__(NWAVES * 64, 2) hymba_fwd(Args args) {
;     extern __shared__ __attribute__((aligned(16))) unsigned char lds_raw[];
;     Ctx C; C.lds = (LAS unsigned char*)lds_raw;
;     C.tid = threadIdx.x; C.lane = C.tid & 63; C.wave = __builtin_amdgcn_readfirstlane(C.tid >> 6);
;     C.G = gridDim.x; { const int bx = blockIdx.x; C.vcu = (C.G % 8 == 0) ? (bx % 8) * (C.G / 8) + bx / 8 : bx; }
;     gu32* ctl = (gu32*)g_ctl;
;     volatile LAS unsigned* MISC = (volatile LAS unsigned*)(C.lds + MISC_OFF);
;     for (int u = C.tid; u < (LDS_BYTES - LDSCTL_OFF) / 4; u += NWAVES * 64) ((LAS unsigned*)(C.lds + LDSCTL_OFF))[u] = 0u;
;     __syncthreads();
;     XcdBarrier bar; bar.bar = (unsigned*)(ctl + CW_BAR); bar.x = 0; bar.st = nullptr;
;     if (N_LAUNCHES != PER_PHASE) bar = xcd_barrier_post((unsigned*)(ctl + CW_BAR), MISC + 8);
;     const int lo = args.ph_lo, hi = args.ph_hi;
_Z9hymba_fwd4Args:
	s_load_dword s3, s[0:1], 0xe8
	s_load_dwordx2 s[86:87], s[0:1], 0xe0
	s_load_dwordx16 s[56:71], s[0:1], 0x0
	s_load_dwordx16 s[12:27], s[0:1], 0x40
	s_load_dwordx16 s[36:51], s[0:1], 0x80
	s_load_dwordx8 s[88:95], s[0:1], 0xc0
	s_add_u32 s96, s0, 0xe8
	s_mov_b32 s83, s2
	s_addc_u32 s97, s1, 0
	s_waitcnt lgkmcnt(0)
	s_and_b32 s2, s3, 7
	v_readfirstlane_b32 s84, v0
	s_mov_b32 s4, 0
	s_cmp_lg_u32 s2, 0
	v_writelane_b32 v249, s83, 0
	s_cbranch_scc1 .LBB0_2
	s_ashr_i32 s5, s83, 31
	s_lshr_b32 s5, s5, 29
	s_add_i32 s5, s83, s5
	s_and_b32 s6, s5, -8
	s_ashr_i32 s2, s3, 3
	s_sub_i32 s6, s83, s6
	s_mul_i32 s2, s2, s6
	s_ashr_i32 s5, s5, 3
	s_add_i32 s2, s2, s5
	v_writelane_b32 v249, s2, 0
.LBB0_2:
	v_lshlrev_b32_e32 v1, 2, v0
	v_add_u32_e32 v2, 0, v1
	s_mov_b32 s5, 1
	s_waitcnt lgkmcnt(0)
	v_writelane_b32 v249, s36, 1
	v_add_u32_e32 v2, 0x23800, v2
	s_mov_b64 s[0:1], 0
	v_writelane_b32 v249, s37, 2
	v_writelane_b32 v249, s38, 3
	v_writelane_b32 v249, s39, 4
	v_writelane_b32 v249, s40, 5
	v_writelane_b32 v249, s41, 6
	v_writelane_b32 v249, s42, 7
	v_writelane_b32 v249, s43, 8
	v_writelane_b32 v249, s44, 9
	v_writelane_b32 v249, s45, 10
	v_writelane_b32 v249, s46, 11
	v_writelane_b32 v249, s47, 12
	v_writelane_b32 v249, s48, 13
	v_writelane_b32 v249, s49, 14
	v_writelane_b32 v249, s50, 15
	v_mov_b32_e32 v3, 0
	s_mov_b32 s6, s4
	v_writelane_b32 v249, s51, 16
	s_branch .LBB0_4
